# plain GEMM ping-pong with merged phases: 32 MFMAs per matrix section (4 hand-overs per K-tile instead of 8), 1+3 LDS-DMA pieces per half K-tile
# speedup vs baseline: 1.0454x; 1.0028x over previous
; #define RAWBAR() { asm volatile("s_waitcnt vmcnt(0) lgkmcnt(0)" ::: "memory"); __builtin_amdgcn_s_barrier(); }
;     ...
;   if (V != 1) GLDS(0, 0);
;   RAWBAR();
;   for (int kt = 0; kt < nk; kt += 2) {
;     if (V != 1) GLDS(kt + 1, 1);
;     if (V != 2) COMPUTE(0);
;     RAWBAR();
;     if (V != 1) if (kt + 2 < nk) GLDS(kt + 2, 0);
;     if (V != 2) COMPUTE(1);
;     RAWBAR();
;   }
.Lgm_pp_lead:
	s_waitcnt vmcnt(0)
	s_barrier
	s_add_u32 m0, s41, 0x10000
	s_nop 0
	global_load_lds_dwordx4 v212, s[24:25]
	s_add_u32 m0, s41, 0x10400
	s_nop 0
	global_load_lds_dwordx4 v213, s[24:25]
	s_add_u32 m0, s14, 0x10000
	s_nop 0
	global_load_lds_dwordx4 v220, s[22:23]
	s_add_u32 m0, s14, 0x10400
	s_nop 0
	global_load_lds_dwordx4 v221, s[22:23]
	s_add_u32 m0, s41, 0x11000
	s_nop 0
	global_load_lds_dwordx4 v214, s[24:25]
	s_add_u32 m0, s41, 0x11400
	s_nop 0
	global_load_lds_dwordx4 v215, s[24:25]
	s_waitcnt vmcnt(6)
	s_barrier
.Lgm_tile:
	s_add_u32 m0, s14, 0x12000
	ds_read_b128 v[162:165], v208
	ds_read_b128 v[166:169], v209
	ds_read_b128 v[170:173], v208 offset:2048
	ds_read_b128 v[174:177], v209 offset:2048
	ds_read_b128 v[224:227], v208 offset:4096
	global_load_lds_dwordx4 v222, s[22:23]
	s_add_u32 m0, s14, 0x12400
	ds_read_b128 v[228:231], v209 offset:4096
	ds_read_b128 v[232:235], v208 offset:6144
	ds_read_b128 v[236:239], v209 offset:6144
	s_waitcnt lgkmcnt(6)
	ds_read_b128 v[128:131], v204
	ds_read_b128 v[132:135], v205
	global_load_lds_dwordx4 v223, s[22:23]
	ds_read_b128 v[136:139], v204 offset:2048
	ds_read_b128 v[140:143], v205 offset:2048
	ds_read_b128 v[144:147], v204 offset:4096
	ds_read_b128 v[148:151], v205 offset:4096
	ds_read_b128 v[152:155], v204 offset:6144
	ds_read_b128 v[156:159], v205 offset:6144
	s_waitcnt lgkmcnt(6)
	s_add_u32 s22, s22, 0x80
	s_addc_u32 s23, s23, 0
	s_add_u32 s24, s24, 0x80
	s_addc_u32 s25, s25, 0
	s_add_u32 s26, s26, 1
	s_cmp_eq_u32 s26, s50
	s_cbranch_scc0 .Lgm_cadv_done2
	s_mov_b32 s26, 0
	s_add_u32 s27, s27, s30
	s_cmp_lt_u32 s27, s29
	s_cbranch_scc1 .Lgm_cadv_new2
	s_lshl_b32 s53, s50, 7
	s_sub_u32 s22, s22, s53
	s_subb_u32 s23, s23, 0
	s_sub_u32 s24, s24, s53
	s_subb_u32 s25, s25, 0
	s_branch .Lgm_cadv_done2

; #define RAWBAR() { asm volatile("s_waitcnt vmcnt(0) lgkmcnt(0)" ::: "memory"); __builtin_amdgcn_s_barrier(); }
;     ...
;   if (V != 1) GLDS(0, 0);
;   RAWBAR();
;   for (int kt = 0; kt < nk; kt += 2) {
;     if (V != 1) GLDS(kt + 1, 1);
;     if (V != 2) COMPUTE(0);
;     RAWBAR();
;     if (V != 1) if (kt + 2 < nk) GLDS(kt + 2, 0);
;     if (V != 2) COMPUTE(1);
;     RAWBAR();
;   }
.Lgm_cadv_done2:
	s_waitcnt lgkmcnt(0)
	s_barrier
	s_setprio 1
	v_mfma_f32_16x16x32_bf16 v[0:3], v[162:165], v[128:131], 0
	v_mfma_f32_16x16x32_bf16 v[0:3], v[166:169], v[132:135], v[0:3]
	v_mfma_f32_16x16x32_bf16 v[4:7], v[170:173], v[128:131], 0
	v_mfma_f32_16x16x32_bf16 v[4:7], v[174:177], v[132:135], v[4:7]
	v_mfma_f32_16x16x32_bf16 v[16:19], v[162:165], v[136:139], 0
	v_mfma_f32_16x16x32_bf16 v[16:19], v[166:169], v[140:143], v[16:19]
	v_mfma_f32_16x16x32_bf16 v[20:23], v[170:173], v[136:139], 0
	v_mfma_f32_16x16x32_bf16 v[20:23], v[174:177], v[140:143], v[20:23]
	v_mfma_f32_16x16x32_bf16 v[32:35], v[162:165], v[144:147], 0
	v_mfma_f32_16x16x32_bf16 v[32:35], v[166:169], v[148:151], v[32:35]
	v_mfma_f32_16x16x32_bf16 v[36:39], v[170:173], v[144:147], 0
	v_mfma_f32_16x16x32_bf16 v[36:39], v[174:177], v[148:151], v[36:39]
	v_mfma_f32_16x16x32_bf16 v[48:51], v[162:165], v[152:155], 0
	v_mfma_f32_16x16x32_bf16 v[48:51], v[166:169], v[156:159], v[48:51]
	v_mfma_f32_16x16x32_bf16 v[52:55], v[170:173], v[152:155], 0
	v_mfma_f32_16x16x32_bf16 v[52:55], v[174:177], v[156:159], v[52:55]
	s_setprio 0
	s_setprio 1
	v_mfma_f32_16x16x32_bf16 v[8:11], v[224:227], v[128:131], 0
	v_mfma_f32_16x16x32_bf16 v[8:11], v[228:231], v[132:135], v[8:11]
	v_mfma_f32_16x16x32_bf16 v[12:15], v[232:235], v[128:131], 0
	v_mfma_f32_16x16x32_bf16 v[12:15], v[236:239], v[132:135], v[12:15]
	v_mfma_f32_16x16x32_bf16 v[24:27], v[224:227], v[136:139], 0
	v_mfma_f32_16x16x32_bf16 v[24:27], v[228:231], v[140:143], v[24:27]
	v_mfma_f32_16x16x32_bf16 v[28:31], v[232:235], v[136:139], 0
	v_mfma_f32_16x16x32_bf16 v[28:31], v[236:239], v[140:143], v[28:31]
	v_mfma_f32_16x16x32_bf16 v[40:43], v[224:227], v[144:147], 0
	v_mfma_f32_16x16x32_bf16 v[40:43], v[228:231], v[148:151], v[40:43]
	v_mfma_f32_16x16x32_bf16 v[44:47], v[232:235], v[144:147], 0
	v_mfma_f32_16x16x32_bf16 v[44:47], v[236:239], v[148:151], v[44:47]
	v_mfma_f32_16x16x32_bf16 v[56:59], v[224:227], v[152:155], 0
	v_mfma_f32_16x16x32_bf16 v[56:59], v[228:231], v[156:159], v[56:59]
	v_mfma_f32_16x16x32_bf16 v[60:63], v[232:235], v[152:155], 0
	v_mfma_f32_16x16x32_bf16 v[60:63], v[236:239], v[156:159], v[60:63]
	s_setprio 0
	s_barrier
	s_add_u32 m0, s41, 0x0
	ds_read_b128 v[128:131], v204 offset:8192
	global_load_lds_dwordx4 v212, s[24:25]
	s_add_u32 m0, s41, 0x400
	ds_read_b128 v[132:135], v205 offset:8192
	global_load_lds_dwordx4 v213, s[24:25]
	s_add_u32 m0, s14, 0x0
	ds_read_b128 v[136:139], v204 offset:10240
	global_load_lds_dwordx4 v220, s[22:23]
	s_add_u32 m0, s14, 0x400
	ds_read_b128 v[140:143], v205 offset:10240
	global_load_lds_dwordx4 v221, s[22:23]
	s_add_u32 m0, s41, 0x1000
	ds_read_b128 v[144:147], v204 offset:12288
	global_load_lds_dwordx4 v214, s[24:25]
	s_add_u32 m0, s41, 0x1400
	ds_read_b128 v[148:151], v205 offset:12288
	global_load_lds_dwordx4 v215, s[24:25]
	ds_read_b128 v[152:155], v204 offset:14336
	ds_read_b128 v[156:159], v205 offset:14336
	s_waitcnt vmcnt(6) lgkmcnt(0)
	s_barrier
	s_setprio 1
	v_mfma_f32_16x16x32_bf16 v[64:67], v[162:165], v[128:131], 0
	v_mfma_f32_16x16x32_bf16 v[64:67], v[166:169], v[132:135], v[64:67]
	v_mfma_f32_16x16x32_bf16 v[68:71], v[170:173], v[128:131], 0
	v_mfma_f32_16x16x32_bf16 v[68:71], v[174:177], v[132:135], v[68:71]
	v_mfma_f32_16x16x32_bf16 v[80:83], v[162:165], v[136:139], 0
	v_mfma_f32_16x16x32_bf16 v[80:83], v[166:169], v[140:143], v[80:83]
	v_mfma_f32_16x16x32_bf16 v[84:87], v[170:173], v[136:139], 0
	v_mfma_f32_16x16x32_bf16 v[84:87], v[174:177], v[140:143], v[84:87]
	v_mfma_f32_16x16x32_bf16 v[96:99], v[162:165], v[144:147], 0
	v_mfma_f32_16x16x32_bf16 v[96:99], v[166:169], v[148:151], v[96:99]
	v_mfma_f32_16x16x32_bf16 v[100:103], v[170:173], v[144:147], 0
	v_mfma_f32_16x16x32_bf16 v[100:103], v[174:177], v[148:151], v[100:103]
	v_mfma_f32_16x16x32_bf16 v[112:115], v[162:165], v[152:155], 0
	v_mfma_f32_16x16x32_bf16 v[112:115], v[166:169], v[156:159], v[112:115]
	v_mfma_f32_16x16x32_bf16 v[116:119], v[170:173], v[152:155], 0
	v_mfma_f32_16x16x32_bf16 v[116:119], v[174:177], v[156:159], v[116:119]
	s_setprio 0
	s_setprio 1
	v_mfma_f32_16x16x32_bf16 v[72:75], v[224:227], v[128:131], 0
	v_mfma_f32_16x16x32_bf16 v[72:75], v[228:231], v[132:135], v[72:75]
	v_mfma_f32_16x16x32_bf16 v[76:79], v[232:235], v[128:131], 0
	v_mfma_f32_16x16x32_bf16 v[76:79], v[236:239], v[132:135], v[76:79]
	v_mfma_f32_16x16x32_bf16 v[88:91], v[224:227], v[136:139], 0
	v_mfma_f32_16x16x32_bf16 v[88:91], v[228:231], v[140:143], v[88:91]
	v_mfma_f32_16x16x32_bf16 v[92:95], v[232:235], v[136:139], 0
	v_mfma_f32_16x16x32_bf16 v[92:95], v[236:239], v[140:143], v[92:95]
	v_mfma_f32_16x16x32_bf16 v[104:107], v[224:227], v[144:147], 0
	v_mfma_f32_16x16x32_bf16 v[104:107], v[228:231], v[148:151], v[104:107]
	v_mfma_f32_16x16x32_bf16 v[108:111], v[232:235], v[144:147], 0
	v_mfma_f32_16x16x32_bf16 v[108:111], v[236:239], v[148:151], v[108:111]
	v_mfma_f32_16x16x32_bf16 v[120:123], v[224:227], v[152:155], 0
	v_mfma_f32_16x16x32_bf16 v[120:123], v[228:231], v[156:159], v[120:123]
	v_mfma_f32_16x16x32_bf16 v[124:127], v[232:235], v[152:155], 0
	v_mfma_f32_16x16x32_bf16 v[124:127], v[236:239], v[156:159], v[124:127]
	s_setprio 0
	s_barrier
	s_add_u32 m0, s14, 0x2000
	ds_read_b128 v[162:165], v210
	ds_read_b128 v[166:169], v211
	ds_read_b128 v[170:173], v210 offset:2048
	ds_read_b128 v[174:177], v211 offset:2048
	ds_read_b128 v[224:227], v210 offset:4096
	global_load_lds_dwordx4 v222, s[22:23]
	s_add_u32 m0, s14, 0x2400
	ds_read_b128 v[228:231], v211 offset:4096
	ds_read_b128 v[232:235], v210 offset:6144
	ds_read_b128 v[236:239], v211 offset:6144
	s_waitcnt lgkmcnt(6)
	ds_read_b128 v[128:131], v206
	ds_read_b128 v[132:135], v207
	global_load_lds_dwordx4 v223, s[22:23]
	ds_read_b128 v[136:139], v206 offset:2048
	ds_read_b128 v[140:143], v207 offset:2048
	ds_read_b128 v[144:147], v206 offset:4096
	ds_read_b128 v[148:151], v207 offset:4096
	ds_read_b128 v[152:155], v206 offset:6144
	ds_read_b128 v[156:159], v207 offset:6144
	s_waitcnt lgkmcnt(6)
	s_add_u32 s22, s22, 0x80
	s_addc_u32 s23, s23, 0
	s_add_u32 s24, s24, 0x80
	s_addc_u32 s25, s25, 0
	s_add_u32 s26, s26, 1
	s_cmp_eq_u32 s26, s50
	s_cbranch_scc0 .Lgm_cadv_done3
	s_mov_b32 s26, 0
	s_add_u32 s27, s27, s30
	s_cmp_lt_u32 s27, s29
	s_cbranch_scc1 .Lgm_cadv_new3
	s_lshl_b32 s53, s50, 7
	s_sub_u32 s22, s22, s53
	s_subb_u32 s23, s23, 0
	s_sub_u32 s24, s24, s53
	s_subb_u32 s25, s25, 0
	s_branch .Lgm_cadv_done3

; #define RAWBAR() { asm volatile("s_waitcnt vmcnt(0) lgkmcnt(0)" ::: "memory"); __builtin_amdgcn_s_barrier(); }
;     ...
;   if (V != 1) GLDS(0, 0);
;   RAWBAR();
;   for (int kt = 0; kt < nk; kt += 2) {
;     if (V != 1) GLDS(kt + 1, 1);
;     if (V != 2) COMPUTE(0);
;     RAWBAR();
;     if (V != 1) if (kt + 2 < nk) GLDS(kt + 2, 0);
;     if (V != 2) COMPUTE(1);
;     RAWBAR();
;   }
.Lgm_cadv_done3:
	s_waitcnt lgkmcnt(0)
	s_barrier
	s_setprio 1
	v_mfma_f32_16x16x32_bf16 v[0:3], v[162:165], v[128:131], v[0:3]
	v_mfma_f32_16x16x32_bf16 v[0:3], v[166:169], v[132:135], v[0:3]
	v_mfma_f32_16x16x32_bf16 v[4:7], v[170:173], v[128:131], v[4:7]
	v_mfma_f32_16x16x32_bf16 v[4:7], v[174:177], v[132:135], v[4:7]
	v_mfma_f32_16x16x32_bf16 v[16:19], v[162:165], v[136:139], v[16:19]
	v_mfma_f32_16x16x32_bf16 v[16:19], v[166:169], v[140:143], v[16:19]
	v_mfma_f32_16x16x32_bf16 v[20:23], v[170:173], v[136:139], v[20:23]
	v_mfma_f32_16x16x32_bf16 v[20:23], v[174:177], v[140:143], v[20:23]
	v_mfma_f32_16x16x32_bf16 v[32:35], v[162:165], v[144:147], v[32:35]
	v_mfma_f32_16x16x32_bf16 v[32:35], v[166:169], v[148:151], v[32:35]
	v_mfma_f32_16x16x32_bf16 v[36:39], v[170:173], v[144:147], v[36:39]
	v_mfma_f32_16x16x32_bf16 v[36:39], v[174:177], v[148:151], v[36:39]
	v_mfma_f32_16x16x32_bf16 v[48:51], v[162:165], v[152:155], v[48:51]
	v_mfma_f32_16x16x32_bf16 v[48:51], v[166:169], v[156:159], v[48:51]
	v_mfma_f32_16x16x32_bf16 v[52:55], v[170:173], v[152:155], v[52:55]
	v_mfma_f32_16x16x32_bf16 v[52:55], v[174:177], v[156:159], v[52:55]
	s_setprio 0
	s_setprio 1
	v_mfma_f32_16x16x32_bf16 v[8:11], v[224:227], v[128:131], v[8:11]
	v_mfma_f32_16x16x32_bf16 v[8:11], v[228:231], v[132:135], v[8:11]
	v_mfma_f32_16x16x32_bf16 v[12:15], v[232:235], v[128:131], v[12:15]
	v_mfma_f32_16x16x32_bf16 v[12:15], v[236:239], v[132:135], v[12:15]
	v_mfma_f32_16x16x32_bf16 v[24:27], v[224:227], v[136:139], v[24:27]
	v_mfma_f32_16x16x32_bf16 v[24:27], v[228:231], v[140:143], v[24:27]
	v_mfma_f32_16x16x32_bf16 v[28:31], v[232:235], v[136:139], v[28:31]
	v_mfma_f32_16x16x32_bf16 v[28:31], v[236:239], v[140:143], v[28:31]
	v_mfma_f32_16x16x32_bf16 v[40:43], v[224:227], v[144:147], v[40:43]
	v_mfma_f32_16x16x32_bf16 v[40:43], v[228:231], v[148:151], v[40:43]
	v_mfma_f32_16x16x32_bf16 v[44:47], v[232:235], v[144:147], v[44:47]
	v_mfma_f32_16x16x32_bf16 v[44:47], v[236:239], v[148:151], v[44:47]
	v_mfma_f32_16x16x32_bf16 v[56:59], v[224:227], v[152:155], v[56:59]
	v_mfma_f32_16x16x32_bf16 v[56:59], v[228:231], v[156:159], v[56:59]
	v_mfma_f32_16x16x32_bf16 v[60:63], v[232:235], v[152:155], v[60:63]
	v_mfma_f32_16x16x32_bf16 v[60:63], v[236:239], v[156:159], v[60:63]
	s_setprio 0
	s_barrier
	s_add_u32 m0, s41, 0x10000
	ds_read_b128 v[128:131], v206 offset:8192
	global_load_lds_dwordx4 v212, s[24:25]
	s_add_u32 m0, s41, 0x10400
	ds_read_b128 v[132:135], v207 offset:8192
	global_load_lds_dwordx4 v213, s[24:25]
	s_add_u32 m0, s14, 0x10000
	ds_read_b128 v[136:139], v206 offset:10240
	global_load_lds_dwordx4 v220, s[22:23]
	s_add_u32 m0, s14, 0x10400
	ds_read_b128 v[140:143], v207 offset:10240
	global_load_lds_dwordx4 v221, s[22:23]
	s_add_u32 m0, s41, 0x11000
	ds_read_b128 v[144:147], v206 offset:12288
	global_load_lds_dwordx4 v214, s[24:25]
	s_add_u32 m0, s41, 0x11400
	ds_read_b128 v[148:151], v207 offset:12288
	global_load_lds_dwordx4 v215, s[24:25]
	ds_read_b128 v[152:155], v206 offset:14336
	ds_read_b128 v[156:159], v207 offset:14336
	s_waitcnt vmcnt(6) lgkmcnt(0)
	s_barrier
	s_setprio 1
	v_mfma_f32_16x16x32_bf16 v[64:67], v[162:165], v[128:131], v[64:67]
	v_mfma_f32_16x16x32_bf16 v[64:67], v[166:169], v[132:135], v[64:67]
	v_mfma_f32_16x16x32_bf16 v[68:71], v[170:173], v[128:131], v[68:71]
	v_mfma_f32_16x16x32_bf16 v[68:71], v[174:177], v[132:135], v[68:71]
	v_mfma_f32_16x16x32_bf16 v[80:83], v[162:165], v[136:139], v[80:83]
	v_mfma_f32_16x16x32_bf16 v[80:83], v[166:169], v[140:143], v[80:83]
	v_mfma_f32_16x16x32_bf16 v[84:87], v[170:173], v[136:139], v[84:87]
	v_mfma_f32_16x16x32_bf16 v[84:87], v[174:177], v[140:143], v[84:87]
	v_mfma_f32_16x16x32_bf16 v[96:99], v[162:165], v[144:147], v[96:99]
	v_mfma_f32_16x16x32_bf16 v[96:99], v[166:169], v[148:151], v[96:99]
	v_mfma_f32_16x16x32_bf16 v[100:103], v[170:173], v[144:147], v[100:103]
	v_mfma_f32_16x16x32_bf16 v[100:103], v[174:177], v[148:151], v[100:103]
	v_mfma_f32_16x16x32_bf16 v[112:115], v[162:165], v[152:155], v[112:115]
	v_mfma_f32_16x16x32_bf16 v[112:115], v[166:169], v[156:159], v[112:115]
	v_mfma_f32_16x16x32_bf16 v[116:119], v[170:173], v[152:155], v[116:119]
	v_mfma_f32_16x16x32_bf16 v[116:119], v[174:177], v[156:159], v[116:119]
	s_setprio 0
	s_setprio 1
	v_mfma_f32_16x16x32_bf16 v[72:75], v[224:227], v[128:131], v[72:75]
	v_mfma_f32_16x16x32_bf16 v[72:75], v[228:231], v[132:135], v[72:75]
	v_mfma_f32_16x16x32_bf16 v[76:79], v[232:235], v[128:131], v[76:79]
	v_mfma_f32_16x16x32_bf16 v[76:79], v[236:239], v[132:135], v[76:79]
	v_mfma_f32_16x16x32_bf16 v[88:91], v[224:227], v[136:139], v[88:91]
	v_mfma_f32_16x16x32_bf16 v[88:91], v[228:231], v[140:143], v[88:91]
	v_mfma_f32_16x16x32_bf16 v[92:95], v[232:235], v[136:139], v[92:95]
	v_mfma_f32_16x16x32_bf16 v[92:95], v[236:239], v[140:143], v[92:95]
	v_mfma_f32_16x16x32_bf16 v[104:107], v[224:227], v[144:147], v[104:107]
	v_mfma_f32_16x16x32_bf16 v[104:107], v[228:231], v[148:151], v[104:107]
	v_mfma_f32_16x16x32_bf16 v[108:111], v[232:235], v[144:147], v[108:111]
	v_mfma_f32_16x16x32_bf16 v[108:111], v[236:239], v[148:151], v[108:111]
	v_mfma_f32_16x16x32_bf16 v[120:123], v[224:227], v[152:155], v[120:123]
	v_mfma_f32_16x16x32_bf16 v[120:123], v[228:231], v[156:159], v[120:123]
	v_mfma_f32_16x16x32_bf16 v[124:127], v[232:235], v[152:155], v[124:127]
	v_mfma_f32_16x16x32_bf16 v[124:127], v[236:239], v[156:159], v[124:127]
	s_setprio 0
	s_barrier
	s_mov_b32 s52, s51
	s_cmp_eq_u32 s52, 0
	s_cbranch_scc1 .Lgm_pairs_done

; #define RAWBAR() { asm volatile("s_waitcnt vmcnt(0) lgkmcnt(0)" ::: "memory"); __builtin_amdgcn_s_barrier(); }
;     ...
;   if (V != 1) GLDS(0, 0);
;   RAWBAR();
;   for (int kt = 0; kt < nk; kt += 2) {
;     if (V != 1) GLDS(kt + 1, 1);
;     if (V != 2) COMPUTE(0);
;     RAWBAR();
;     if (V != 1) if (kt + 2 < nk) GLDS(kt + 2, 0);
;     if (V != 2) COMPUTE(1);
;     RAWBAR();
;   }
.Lgm_cadv_done4:
	s_waitcnt lgkmcnt(0)
	s_barrier
	s_setprio 1
	v_mfma_f32_16x16x32_bf16 v[0:3], v[162:165], v[128:131], v[0:3]
	v_mfma_f32_16x16x32_bf16 v[0:3], v[166:169], v[132:135], v[0:3]
	v_mfma_f32_16x16x32_bf16 v[4:7], v[170:173], v[128:131], v[4:7]
	v_mfma_f32_16x16x32_bf16 v[4:7], v[174:177], v[132:135], v[4:7]
	v_mfma_f32_16x16x32_bf16 v[16:19], v[162:165], v[136:139], v[16:19]
	v_mfma_f32_16x16x32_bf16 v[16:19], v[166:169], v[140:143], v[16:19]
	v_mfma_f32_16x16x32_bf16 v[20:23], v[170:173], v[136:139], v[20:23]
	v_mfma_f32_16x16x32_bf16 v[20:23], v[174:177], v[140:143], v[20:23]
	v_mfma_f32_16x16x32_bf16 v[32:35], v[162:165], v[144:147], v[32:35]
	v_mfma_f32_16x16x32_bf16 v[32:35], v[166:169], v[148:151], v[32:35]
	v_mfma_f32_16x16x32_bf16 v[36:39], v[170:173], v[144:147], v[36:39]
	v_mfma_f32_16x16x32_bf16 v[36:39], v[174:177], v[148:151], v[36:39]
	v_mfma_f32_16x16x32_bf16 v[48:51], v[162:165], v[152:155], v[48:51]
	v_mfma_f32_16x16x32_bf16 v[48:51], v[166:169], v[156:159], v[48:51]
	v_mfma_f32_16x16x32_bf16 v[52:55], v[170:173], v[152:155], v[52:55]
	v_mfma_f32_16x16x32_bf16 v[52:55], v[174:177], v[156:159], v[52:55]
	s_setprio 0
	s_setprio 1
	v_mfma_f32_16x16x32_bf16 v[8:11], v[224:227], v[128:131], v[8:11]
	v_mfma_f32_16x16x32_bf16 v[8:11], v[228:231], v[132:135], v[8:11]
	v_mfma_f32_16x16x32_bf16 v[12:15], v[232:235], v[128:131], v[12:15]
	v_mfma_f32_16x16x32_bf16 v[12:15], v[236:239], v[132:135], v[12:15]
	v_mfma_f32_16x16x32_bf16 v[24:27], v[224:227], v[136:139], v[24:27]
	v_mfma_f32_16x16x32_bf16 v[24:27], v[228:231], v[140:143], v[24:27]
	v_mfma_f32_16x16x32_bf16 v[28:31], v[232:235], v[136:139], v[28:31]
	v_mfma_f32_16x16x32_bf16 v[28:31], v[236:239], v[140:143], v[28:31]
	v_mfma_f32_16x16x32_bf16 v[40:43], v[224:227], v[144:147], v[40:43]
	v_mfma_f32_16x16x32_bf16 v[40:43], v[228:231], v[148:151], v[40:43]
	v_mfma_f32_16x16x32_bf16 v[44:47], v[232:235], v[144:147], v[44:47]
	v_mfma_f32_16x16x32_bf16 v[44:47], v[236:239], v[148:151], v[44:47]
	v_mfma_f32_16x16x32_bf16 v[56:59], v[224:227], v[152:155], v[56:59]
	v_mfma_f32_16x16x32_bf16 v[56:59], v[228:231], v[156:159], v[56:59]
	v_mfma_f32_16x16x32_bf16 v[60:63], v[232:235], v[152:155], v[60:63]
	v_mfma_f32_16x16x32_bf16 v[60:63], v[236:239], v[156:159], v[60:63]
	s_setprio 0
	s_barrier
	s_add_u32 m0, s41, 0x0
	ds_read_b128 v[128:131], v204 offset:8192
	global_load_lds_dwordx4 v212, s[24:25]
	s_add_u32 m0, s41, 0x400
	ds_read_b128 v[132:135], v205 offset:8192
	global_load_lds_dwordx4 v213, s[24:25]
	s_add_u32 m0, s14, 0x0
	ds_read_b128 v[136:139], v204 offset:10240
	global_load_lds_dwordx4 v220, s[22:23]
	s_add_u32 m0, s14, 0x400
	ds_read_b128 v[140:143], v205 offset:10240
	global_load_lds_dwordx4 v221, s[22:23]
	s_add_u32 m0, s41, 0x1000
	ds_read_b128 v[144:147], v204 offset:12288
	global_load_lds_dwordx4 v214, s[24:25]
	s_add_u32 m0, s41, 0x1400
	ds_read_b128 v[148:151], v205 offset:12288
	global_load_lds_dwordx4 v215, s[24:25]
	ds_read_b128 v[152:155], v204 offset:14336
	ds_read_b128 v[156:159], v205 offset:14336
	s_waitcnt vmcnt(6) lgkmcnt(0)
	s_barrier
	s_setprio 1
	v_mfma_f32_16x16x32_bf16 v[64:67], v[162:165], v[128:131], v[64:67]
	v_mfma_f32_16x16x32_bf16 v[64:67], v[166:169], v[132:135], v[64:67]
	v_mfma_f32_16x16x32_bf16 v[68:71], v[170:173], v[128:131], v[68:71]
	v_mfma_f32_16x16x32_bf16 v[68:71], v[174:177], v[132:135], v[68:71]
	v_mfma_f32_16x16x32_bf16 v[80:83], v[162:165], v[136:139], v[80:83]
	v_mfma_f32_16x16x32_bf16 v[80:83], v[166:169], v[140:143], v[80:83]
	v_mfma_f32_16x16x32_bf16 v[84:87], v[170:173], v[136:139], v[84:87]
	v_mfma_f32_16x16x32_bf16 v[84:87], v[174:177], v[140:143], v[84:87]
	v_mfma_f32_16x16x32_bf16 v[96:99], v[162:165], v[144:147], v[96:99]
	v_mfma_f32_16x16x32_bf16 v[96:99], v[166:169], v[148:151], v[96:99]
	v_mfma_f32_16x16x32_bf16 v[100:103], v[170:173], v[144:147], v[100:103]
	v_mfma_f32_16x16x32_bf16 v[100:103], v[174:177], v[148:151], v[100:103]
	v_mfma_f32_16x16x32_bf16 v[112:115], v[162:165], v[152:155], v[112:115]
	v_mfma_f32_16x16x32_bf16 v[112:115], v[166:169], v[156:159], v[112:115]
	v_mfma_f32_16x16x32_bf16 v[116:119], v[170:173], v[152:155], v[116:119]
	v_mfma_f32_16x16x32_bf16 v[116:119], v[174:177], v[156:159], v[116:119]
	s_setprio 0
	s_setprio 1
	v_mfma_f32_16x16x32_bf16 v[72:75], v[224:227], v[128:131], v[72:75]
	v_mfma_f32_16x16x32_bf16 v[72:75], v[228:231], v[132:135], v[72:75]
	v_mfma_f32_16x16x32_bf16 v[76:79], v[232:235], v[128:131], v[76:79]
	v_mfma_f32_16x16x32_bf16 v[76:79], v[236:239], v[132:135], v[76:79]
	v_mfma_f32_16x16x32_bf16 v[88:91], v[224:227], v[136:139], v[88:91]
	v_mfma_f32_16x16x32_bf16 v[88:91], v[228:231], v[140:143], v[88:91]
	v_mfma_f32_16x16x32_bf16 v[92:95], v[232:235], v[136:139], v[92:95]
	v_mfma_f32_16x16x32_bf16 v[92:95], v[236:239], v[140:143], v[92:95]
	v_mfma_f32_16x16x32_bf16 v[104:107], v[224:227], v[144:147], v[104:107]
	v_mfma_f32_16x16x32_bf16 v[104:107], v[228:231], v[148:151], v[104:107]
	v_mfma_f32_16x16x32_bf16 v[108:111], v[232:235], v[144:147], v[108:111]
	v_mfma_f32_16x16x32_bf16 v[108:111], v[236:239], v[148:151], v[108:111]
	v_mfma_f32_16x16x32_bf16 v[120:123], v[224:227], v[152:155], v[120:123]
	v_mfma_f32_16x16x32_bf16 v[120:123], v[228:231], v[156:159], v[120:123]
	v_mfma_f32_16x16x32_bf16 v[124:127], v[232:235], v[152:155], v[124:127]
	v_mfma_f32_16x16x32_bf16 v[124:127], v[236:239], v[156:159], v[124:127]
	s_setprio 0
	s_barrier
	s_add_u32 m0, s14, 0x2000
	ds_read_b128 v[162:165], v210
	ds_read_b128 v[166:169], v211
	ds_read_b128 v[170:173], v210 offset:2048
	ds_read_b128 v[174:177], v211 offset:2048
	ds_read_b128 v[224:227], v210 offset:4096
	global_load_lds_dwordx4 v222, s[22:23]
	s_add_u32 m0, s14, 0x2400
	ds_read_b128 v[228:231], v211 offset:4096
	ds_read_b128 v[232:235], v210 offset:6144
	ds_read_b128 v[236:239], v211 offset:6144
	s_waitcnt lgkmcnt(6)
	ds_read_b128 v[128:131], v206
	ds_read_b128 v[132:135], v207
	global_load_lds_dwordx4 v223, s[22:23]
	ds_read_b128 v[136:139], v206 offset:2048
	ds_read_b128 v[140:143], v207 offset:2048
	ds_read_b128 v[144:147], v206 offset:4096
	ds_read_b128 v[148:151], v207 offset:4096
	ds_read_b128 v[152:155], v206 offset:6144
	ds_read_b128 v[156:159], v207 offset:6144
	s_waitcnt lgkmcnt(6)
	s_add_u32 s22, s22, 0x80
	s_addc_u32 s23, s23, 0
	s_add_u32 s24, s24, 0x80
	s_addc_u32 s25, s25, 0
	s_add_u32 s26, s26, 1
	s_cmp_eq_u32 s26, s50
	s_cbranch_scc0 .Lgm_cadv_done5
	s_mov_b32 s26, 0
	s_add_u32 s27, s27, s30
	s_cmp_lt_u32 s27, s29
	s_cbranch_scc1 .Lgm_cadv_new5
	s_lshl_b32 s53, s50, 7
	s_sub_u32 s22, s22, s53
	s_subb_u32 s23, s23, 0
	s_sub_u32 s24, s24, s53
	s_subb_u32 s25, s25, 0
	s_branch .Lgm_cadv_done5

; #define RAWBAR() { asm volatile("s_waitcnt vmcnt(0) lgkmcnt(0)" ::: "memory"); __builtin_amdgcn_s_barrier(); }
;     ...
;   if (V != 1) GLDS(0, 0);
;   RAWBAR();
;   for (int kt = 0; kt < nk; kt += 2) {
;     if (V != 1) GLDS(kt + 1, 1);
;     if (V != 2) COMPUTE(0);
;     RAWBAR();
;     if (V != 1) if (kt + 2 < nk) GLDS(kt + 2, 0);
;     if (V != 2) COMPUTE(1);
;     RAWBAR();
;   }
.Lgm_cadv_done5:
	s_waitcnt lgkmcnt(0)
	s_barrier
	s_setprio 1
	v_mfma_f32_16x16x32_bf16 v[0:3], v[162:165], v[128:131], v[0:3]
	v_mfma_f32_16x16x32_bf16 v[0:3], v[166:169], v[132:135], v[0:3]
	v_mfma_f32_16x16x32_bf16 v[4:7], v[170:173], v[128:131], v[4:7]
	v_mfma_f32_16x16x32_bf16 v[4:7], v[174:177], v[132:135], v[4:7]
	v_mfma_f32_16x16x32_bf16 v[16:19], v[162:165], v[136:139], v[16:19]
	v_mfma_f32_16x16x32_bf16 v[16:19], v[166:169], v[140:143], v[16:19]
	v_mfma_f32_16x16x32_bf16 v[20:23], v[170:173], v[136:139], v[20:23]
	v_mfma_f32_16x16x32_bf16 v[20:23], v[174:177], v[140:143], v[20:23]
	v_mfma_f32_16x16x32_bf16 v[32:35], v[162:165], v[144:147], v[32:35]
	v_mfma_f32_16x16x32_bf16 v[32:35], v[166:169], v[148:151], v[32:35]
	v_mfma_f32_16x16x32_bf16 v[36:39], v[170:173], v[144:147], v[36:39]
	v_mfma_f32_16x16x32_bf16 v[36:39], v[174:177], v[148:151], v[36:39]
	v_mfma_f32_16x16x32_bf16 v[48:51], v[162:165], v[152:155], v[48:51]
	v_mfma_f32_16x16x32_bf16 v[48:51], v[166:169], v[156:159], v[48:51]
	v_mfma_f32_16x16x32_bf16 v[52:55], v[170:173], v[152:155], v[52:55]
	v_mfma_f32_16x16x32_bf16 v[52:55], v[174:177], v[156:159], v[52:55]
	s_setprio 0
	s_setprio 1
	v_mfma_f32_16x16x32_bf16 v[8:11], v[224:227], v[128:131], v[8:11]
	v_mfma_f32_16x16x32_bf16 v[8:11], v[228:231], v[132:135], v[8:11]
	v_mfma_f32_16x16x32_bf16 v[12:15], v[232:235], v[128:131], v[12:15]
	v_mfma_f32_16x16x32_bf16 v[12:15], v[236:239], v[132:135], v[12:15]
	v_mfma_f32_16x16x32_bf16 v[24:27], v[224:227], v[136:139], v[24:27]
	v_mfma_f32_16x16x32_bf16 v[24:27], v[228:231], v[140:143], v[24:27]
	v_mfma_f32_16x16x32_bf16 v[28:31], v[232:235], v[136:139], v[28:31]
	v_mfma_f32_16x16x32_bf16 v[28:31], v[236:239], v[140:143], v[28:31]
	v_mfma_f32_16x16x32_bf16 v[40:43], v[224:227], v[144:147], v[40:43]
	v_mfma_f32_16x16x32_bf16 v[40:43], v[228:231], v[148:151], v[40:43]
	v_mfma_f32_16x16x32_bf16 v[44:47], v[232:235], v[144:147], v[44:47]
	v_mfma_f32_16x16x32_bf16 v[44:47], v[236:239], v[148:151], v[44:47]
	v_mfma_f32_16x16x32_bf16 v[56:59], v[224:227], v[152:155], v[56:59]
	v_mfma_f32_16x16x32_bf16 v[56:59], v[228:231], v[156:159], v[56:59]
	v_mfma_f32_16x16x32_bf16 v[60:63], v[232:235], v[152:155], v[60:63]
	v_mfma_f32_16x16x32_bf16 v[60:63], v[236:239], v[156:159], v[60:63]
	s_setprio 0
	s_barrier
	s_add_u32 m0, s41, 0x10000
	ds_read_b128 v[128:131], v206 offset:8192
	global_load_lds_dwordx4 v212, s[24:25]
	s_add_u32 m0, s41, 0x10400
	ds_read_b128 v[132:135], v207 offset:8192
	global_load_lds_dwordx4 v213, s[24:25]
	s_add_u32 m0, s14, 0x10000
	ds_read_b128 v[136:139], v206 offset:10240
	global_load_lds_dwordx4 v220, s[22:23]
	s_add_u32 m0, s14, 0x10400
	ds_read_b128 v[140:143], v207 offset:10240
	global_load_lds_dwordx4 v221, s[22:23]
	s_add_u32 m0, s41, 0x11000
	ds_read_b128 v[144:147], v206 offset:12288
	global_load_lds_dwordx4 v214, s[24:25]
	s_add_u32 m0, s41, 0x11400
	ds_read_b128 v[148:151], v207 offset:12288
	global_load_lds_dwordx4 v215, s[24:25]
	ds_read_b128 v[152:155], v206 offset:14336
	ds_read_b128 v[156:159], v207 offset:14336
	s_waitcnt vmcnt(6) lgkmcnt(0)
	s_barrier
	s_setprio 1
	v_mfma_f32_16x16x32_bf16 v[64:67], v[162:165], v[128:131], v[64:67]
	v_mfma_f32_16x16x32_bf16 v[64:67], v[166:169], v[132:135], v[64:67]
	v_mfma_f32_16x16x32_bf16 v[68:71], v[170:173], v[128:131], v[68:71]
	v_mfma_f32_16x16x32_bf16 v[68:71], v[174:177], v[132:135], v[68:71]
	v_mfma_f32_16x16x32_bf16 v[80:83], v[162:165], v[136:139], v[80:83]
	v_mfma_f32_16x16x32_bf16 v[80:83], v[166:169], v[140:143], v[80:83]
	v_mfma_f32_16x16x32_bf16 v[84:87], v[170:173], v[136:139], v[84:87]
	v_mfma_f32_16x16x32_bf16 v[84:87], v[174:177], v[140:143], v[84:87]
	v_mfma_f32_16x16x32_bf16 v[96:99], v[162:165], v[144:147], v[96:99]
	v_mfma_f32_16x16x32_bf16 v[96:99], v[166:169], v[148:151], v[96:99]
	v_mfma_f32_16x16x32_bf16 v[100:103], v[170:173], v[144:147], v[100:103]
	v_mfma_f32_16x16x32_bf16 v[100:103], v[174:177], v[148:151], v[100:103]
	v_mfma_f32_16x16x32_bf16 v[112:115], v[162:165], v[152:155], v[112:115]
	v_mfma_f32_16x16x32_bf16 v[112:115], v[166:169], v[156:159], v[112:115]
	v_mfma_f32_16x16x32_bf16 v[116:119], v[170:173], v[152:155], v[116:119]
	v_mfma_f32_16x16x32_bf16 v[116:119], v[174:177], v[156:159], v[116:119]
	s_setprio 0
	s_setprio 1
	v_mfma_f32_16x16x32_bf16 v[72:75], v[224:227], v[128:131], v[72:75]
	v_mfma_f32_16x16x32_bf16 v[72:75], v[228:231], v[132:135], v[72:75]
	v_mfma_f32_16x16x32_bf16 v[76:79], v[232:235], v[128:131], v[76:79]
	v_mfma_f32_16x16x32_bf16 v[76:79], v[236:239], v[132:135], v[76:79]
	v_mfma_f32_16x16x32_bf16 v[88:91], v[224:227], v[136:139], v[88:91]
	v_mfma_f32_16x16x32_bf16 v[88:91], v[228:231], v[140:143], v[88:91]
	v_mfma_f32_16x16x32_bf16 v[92:95], v[232:235], v[136:139], v[92:95]
	v_mfma_f32_16x16x32_bf16 v[92:95], v[236:239], v[140:143], v[92:95]
	v_mfma_f32_16x16x32_bf16 v[104:107], v[224:227], v[144:147], v[104:107]
	v_mfma_f32_16x16x32_bf16 v[104:107], v[228:231], v[148:151], v[104:107]
	v_mfma_f32_16x16x32_bf16 v[108:111], v[232:235], v[144:147], v[108:111]
	v_mfma_f32_16x16x32_bf16 v[108:111], v[236:239], v[148:151], v[108:111]
	v_mfma_f32_16x16x32_bf16 v[120:123], v[224:227], v[152:155], v[120:123]
	v_mfma_f32_16x16x32_bf16 v[120:123], v[228:231], v[156:159], v[120:123]
	v_mfma_f32_16x16x32_bf16 v[124:127], v[232:235], v[152:155], v[124:127]
	v_mfma_f32_16x16x32_bf16 v[124:127], v[236:239], v[156:159], v[124:127]
	s_setprio 0
	s_barrier
	s_sub_u32 s52, s52, 1
	s_cmp_lg_u32 s52, 0
	s_cbranch_scc1 .Lgm_pair
